# collective copy engines: 16 groups per grab at P2 and P7, 8 at P5 (HBM-tight phase); tid and grid size read from the persistent copies
# speedup vs baseline: 1.0200x; 1.0200x over previous
.LBB0_175:
	s_nop 0
	v_readlane_b32 s4, v242, 2
	v_readlane_b32 s6, v242, 4
	v_readlane_b32 s7, v242, 5
	s_add_u32 s0, s6, 0x2000
	s_addc_u32 s1, s7, 0
	v_readlane_b32 s5, v242, 3
	v_writelane_b32 v242, s0, 43
	v_lshlrev_b32_e32 v148, 4, v0
	s_nop 0
	v_writelane_b32 v242, s1, 44
	s_add_u32 s0, s6, 0x6200000
	s_addc_u32 s1, s7, 0
	v_writelane_b32 v242, s0, 45
	s_nop 1
	v_writelane_b32 v242, s1, 46
	s_add_u32 s0, s6, 0xa400000
	s_addc_u32 s1, s7, 0
	v_writelane_b32 v242, s0, 47
	s_nop 1
	v_writelane_b32 v242, s1, 48
	s_add_u32 s0, s6, 0x2d500000
	s_addc_u32 s1, s7, 0
	v_writelane_b32 v242, s0, 49
	s_nop 1
	v_writelane_b32 v242, s1, 50
	s_add_u32 s0, s6, 0x2f600000
	s_addc_u32 s1, s7, 0
	v_writelane_b32 v242, s0, 51
	s_nop 1
	v_writelane_b32 v242, s1, 52
	s_add_u32 s0, s6, 0x31700000
	s_addc_u32 s1, s7, 0
	s_cmpk_eq_i32 s84, 0x100
	v_writelane_b32 v242, s0, 53
	s_cselect_b64 s[58:59], -1, 0
	s_cmp_lt_i32 s72, 3
	v_writelane_b32 v242, s1, 54
	s_cselect_b64 s[0:1], -1, 0
	s_cmp_gt_i32 s73, 2
	s_cselect_b64 s[2:3], -1, 0
	s_and_b64 s[0:1], s[0:1], s[2:3]
	v_writelane_b32 v242, s92, 55
	s_andn2_b64 vcc, exec, s[0:1]
	s_mov_b32 s0, s84
	v_writelane_b32 v242, s93, 56
	v_writelane_b32 v242, s0, 57
	v_writelane_b32 v241, s58, 0
	s_nop 0
	v_writelane_b32 v242, s1, 58
	v_writelane_b32 v242, s72, 59
	s_mov_b32 s0, s88
	v_writelane_b32 v241, s59, 1
	v_writelane_b32 v242, s73, 60
	v_writelane_b32 v242, s0, 61
	s_nop 1
	v_writelane_b32 v242, s1, 62
	v_writelane_b32 v242, s74, 63
	s_cbranch_vccnz .LBB0_607
	s_and_b64 s[0:1], s[58:59], exec
	s_cselect_b32 s33, 0xd8, s84
	s_add_u32 s0, s6, 0x5400
	s_addc_u32 s1, s7, 0
	v_writelane_b32 v241, s0, 2
	v_mov_b32_e32 v149, 0
	v_lshl_add_u64 v[152:153], s[4:5], 0, v[148:149]
	v_writelane_b32 v241, s1, 3
	s_add_u32 s0, s6, 0x5500
	s_addc_u32 s1, s7, 0
	v_writelane_b32 v241, s0, 4
	s_nop 1
	v_writelane_b32 v241, s1, 5
	s_add_u32 s0, s6, 0x5600
	s_addc_u32 s1, s7, 0
	v_writelane_b32 v241, s0, 6
	s_nop 1
	v_writelane_b32 v241, s1, 7
	s_add_u32 s0, s6, 0x5700
	s_addc_u32 s1, s7, 0
	v_writelane_b32 v241, s0, 8
	s_nop 1
	v_writelane_b32 v241, s1, 9
	s_add_u32 s0, s6, 0x5800
	s_addc_u32 s1, s7, 0
	v_writelane_b32 v241, s0, 10
	s_nop 1
	v_writelane_b32 v241, s1, 11
	s_add_u32 s0, s6, 0x5900
	s_addc_u32 s1, s7, 0
	s_add_u32 s34, s6, 0x5a00
	s_addc_u32 s35, s7, 0
	s_add_u32 s40, s6, 0x5b00
	s_addc_u32 s41, s7, 0
	s_add_u32 s42, s6, 0x5c00
	s_addc_u32 s43, s7, 0
	s_add_u32 s50, s6, 0x5d00
	s_addc_u32 s51, s7, 0
	s_add_u32 s56, s6, 0x5e00
	s_addc_u32 s57, s7, 0
	s_add_u32 s60, s6, 0x5f00
	s_addc_u32 s61, s7, 0
	s_add_u32 s62, s6, 0x6000
	s_addc_u32 s63, s7, 0
	s_add_u32 s64, s6, 0x6100
	s_addc_u32 s65, s7, 0
	s_add_u32 s68, s6, 0x6200
	s_addc_u32 s69, s7, 0
	s_add_u32 s70, s6, 0x6300
	s_addc_u32 s71, s7, 0
	s_ashr_i32 s54, s33, 31
	v_writelane_b32 v241, s0, 12
	s_cmp_gt_u32 s73, 3
	s_nop 0
	v_writelane_b32 v241, s1, 13
	s_cselect_b64 s[0:1], -1, 0
	v_writelane_b32 v241, s0, 14
	s_cmp_lt_i32 s92, s33
	s_nop 0
	v_writelane_b32 v241, s1, 15
	s_mov_b64 s[0:1], -1
	s_cbranch_scc1 .LBB0_210
	v_mov_b32_e32 v104, v148
	v_add_u32_e32 v105, 0x2000, v104
	v_add_u32_e32 v106, 0x4000, v104
	v_add_u32_e32 v107, 0x6000, v104
	v_add_u32_e32 v108, 0x8000, v104
	v_add_u32_e32 v109, 0xa000, v104
	v_add_u32_e32 v110, 0xc000, v104
	v_add_u32_e32 v111, 0xe000, v104
	v_add_u32_e32 v112, 0x10000, v104
	v_add_u32_e32 v113, 0x12000, v104
	v_add_u32_e32 v114, 0x14000, v104
	v_add_u32_e32 v115, 0x16000, v104
	v_add_u32_e32 v116, 0x18000, v104
	v_add_u32_e32 v117, 0x1a000, v104
	v_add_u32_e32 v118, 0x1c000, v104
	v_add_u32_e32 v119, 0x1e000, v104
	v_lshrrev_b32_e32 v5, 10, v148
	v_readlane_b32 s56, v242, 43
	v_readlane_b32 s57, v242, 44
	v_readlane_b32 s60, v242, 2
	v_readlane_b32 s61, v242, 3
	v_readlane_b32 s66, v242, 4
	v_readlane_b32 s67, v242, 5
	v_readlane_b32 s68, v242, 25
	v_readfirstlane_b32 s70, v5
	v_mov_b32_e32 v2, 0
	v_mov_b32_e32 v3, 16
	v_mov_b32_e32 v6, 0x20180
	s_mov_b32 s64, 0x10478000
	s_mov_b32 s65, 0x30478000
	s_add_u32 s66, s66, 0x5400
	s_addc_u32 s67, s67, 0
	v_readlane_b32 s69, v242, 57
	s_nop 3
	s_mul_i32 s68, s68, s69
	s_mov_b64 s[62:63], exec
	s_mov_b32 s71, 0
	s_cmp_lg_u32 s70, 0
	s_cbranch_scc1 .Lce_first_done_P2
	s_mov_b64 exec, 1
	global_atomic_add v4, v2, v3, s[56:57] sc0
	s_waitcnt vmcnt(0)
	ds_write_b32 v6, v4
	s_waitcnt lgkmcnt(0)
	s_mov_b64 exec, s[62:63]

.LBB0_1752:
	s_nop 0
	v_readlane_b32 s4, v242, 2
	v_readlane_b32 s6, v242, 4
	v_readlane_b32 s7, v242, 5
	s_add_u32 s0, s6, 0x14900000
	s_addc_u32 s1, s7, 0
	v_readlane_b32 s5, v242, 3
	v_writelane_b32 v242, s0, 47
	s_cmp_lt_i32 s72, 6
	s_nop 0
	v_writelane_b32 v242, s1, 48
	s_cselect_b64 s[0:1], -1, 0
	s_cmp_gt_i32 s73, 5
	s_cselect_b64 s[2:3], -1, 0
	s_and_b64 s[0:1], s[0:1], s[2:3]
	s_andn2_b64 vcc, exec, s[0:1]
	s_cbranch_vccnz .LBB0_1891
	s_and_b64 s[0:1], s[58:59], exec
	s_cselect_b32 s33, 0xb0, s84
	s_add_u32 s0, s6, 0x5400
	s_addc_u32 s1, s7, 0
	v_writelane_b32 v242, s0, 30
	v_mov_b32_e32 v149, 0
	v_lshl_add_u64 v[134:135], s[4:5], 0, v[148:149]
	v_writelane_b32 v242, s1, 31
	s_add_u32 s0, s6, 0x5500
	s_addc_u32 s1, s7, 0
	v_writelane_b32 v241, s0, 2
	s_mov_b64 s[4:5], -1
	s_nop 0
	v_writelane_b32 v241, s1, 3
	s_add_u32 s0, s6, 0x5600
	s_addc_u32 s1, s7, 0
	v_writelane_b32 v241, s0, 4
	s_nop 1
	v_writelane_b32 v241, s1, 5
	s_add_u32 s0, s6, 0x5700
	s_addc_u32 s1, s7, 0
	v_writelane_b32 v241, s0, 6
	s_nop 1
	v_writelane_b32 v241, s1, 7
	s_add_u32 s0, s6, 0x5800
	s_addc_u32 s1, s7, 0
	s_add_u32 s14, s6, 0x5900
	s_addc_u32 s15, s7, 0
	s_add_u32 s16, s6, 0x5a00
	s_addc_u32 s17, s7, 0
	s_add_u32 s18, s6, 0x5b00
	s_addc_u32 s19, s7, 0
	s_add_u32 s20, s6, 0x5c00
	s_addc_u32 s21, s7, 0
	s_add_u32 s22, s6, 0x5d00
	s_addc_u32 s23, s7, 0
	s_add_u32 s24, s6, 0x5e00
	s_addc_u32 s25, s7, 0
	s_add_u32 s26, s6, 0x5f00
	s_addc_u32 s27, s7, 0
	s_add_u32 s28, s6, 0x6000
	s_addc_u32 s29, s7, 0
	s_add_u32 s30, s6, 0x6100
	s_addc_u32 s31, s7, 0
	s_add_u32 s34, s6, 0x6200
	s_addc_u32 s35, s7, 0
	s_add_u32 s40, s6, 0x6300
	s_addc_u32 s41, s7, 0
	s_ashr_i32 s42, s33, 31
	v_writelane_b32 v241, s0, 8
	s_cmp_gt_u32 s73, 6
	s_nop 0
	v_writelane_b32 v241, s1, 9
	s_cselect_b64 s[0:1], -1, 0
	v_writelane_b32 v241, s0, 10
	s_cmp_lt_i32 s92, s33
	s_nop 0
	v_writelane_b32 v241, s1, 11
	s_cbranch_scc1 .LBB0_1787
	v_mov_b32_e32 v104, v148
	v_add_u32_e32 v105, 0x2000, v104
	v_add_u32_e32 v106, 0x4000, v104
	v_add_u32_e32 v107, 0x6000, v104
	v_add_u32_e32 v108, 0x8000, v104
	v_add_u32_e32 v109, 0xa000, v104
	v_add_u32_e32 v110, 0xc000, v104
	v_add_u32_e32 v111, 0xe000, v104
	v_lshrrev_b32_e32 v5, 10, v148
	v_readlane_b32 s56, v242, 43
	v_readlane_b32 s57, v242, 44
	v_readlane_b32 s60, v242, 2
	v_readlane_b32 s61, v242, 3
	v_readlane_b32 s66, v242, 4
	v_readlane_b32 s67, v242, 5
	v_readlane_b32 s68, v242, 25
	v_readfirstlane_b32 s70, v5
	v_mov_b32_e32 v2, 0
	v_mov_b32_e32 v3, 8
	v_mov_b32_e32 v6, 0x20180
	s_mov_b32 s64, 0x10478000
	s_mov_b32 s65, 0x30478000
	s_add_u32 s66, s66, 0x5400
	s_addc_u32 s67, s67, 0
	v_readlane_b32 s69, v242, 57
	s_nop 3
	s_mul_i32 s68, s68, s69
	s_mov_b64 s[62:63], exec
	s_mov_b32 s71, 0
	s_cmp_lg_u32 s70, 0
	s_cbranch_scc1 .Lce_first_done_P5
	s_mov_b64 exec, 1
	global_atomic_add v4, v2, v3, s[56:57] sc0
	s_waitcnt vmcnt(0)
	ds_write_b32 v6, v4
	s_waitcnt lgkmcnt(0)
	s_mov_b64 exec, s[62:63]

.LBB0_1957:
	s_nop 0
	v_readlane_b32 s8, v242, 2
	v_readlane_b32 s10, v242, 4
	v_readlane_b32 s11, v242, 5
	s_add_u32 s2, s10, 0x1cd00000
	s_addc_u32 s3, s11, 0
	s_cmp_lt_i32 s72, 8
	s_cselect_b64 s[0:1], -1, 0
	s_cmp_gt_i32 s73, 7
	s_cselect_b64 s[4:5], -1, 0
	s_and_b64 s[0:1], s[0:1], s[4:5]
	v_readlane_b32 s9, v242, 3
	s_andn2_b64 vcc, exec, s[0:1]
	s_cbranch_vccnz .LBB0_2096
	s_and_b64 s[0:1], s[58:59], exec
	s_cselect_b32 s33, 0xf0, s84
	s_add_u32 s0, s10, 0x5400
	s_addc_u32 s1, s11, 0
	v_writelane_b32 v242, s0, 30
	v_mov_b32_e32 v149, 0
	v_lshl_add_u64 v[130:131], s[8:9], 0, v[148:149]
	v_writelane_b32 v242, s1, 31
	s_add_u32 s0, s10, 0x5500
	s_addc_u32 s1, s11, 0
	v_writelane_b32 v241, s0, 2
	s_mov_b64 s[4:5], -1
	s_nop 0
	v_writelane_b32 v241, s1, 3
	s_add_u32 s0, s10, 0x5600
	s_addc_u32 s1, s11, 0
	v_writelane_b32 v241, s0, 4
	s_nop 1
	v_writelane_b32 v241, s1, 5
	s_add_u32 s0, s10, 0x5700
	s_addc_u32 s1, s11, 0
	s_add_u32 s14, s10, 0x5800
	s_addc_u32 s15, s11, 0
	s_add_u32 s16, s10, 0x5900
	s_addc_u32 s17, s11, 0
	s_add_u32 s18, s10, 0x5a00
	s_addc_u32 s19, s11, 0
	s_add_u32 s20, s10, 0x5b00
	s_addc_u32 s21, s11, 0
	s_add_u32 s22, s10, 0x5c00
	s_addc_u32 s23, s11, 0
	s_add_u32 s24, s10, 0x5d00
	s_addc_u32 s25, s11, 0
	s_add_u32 s26, s10, 0x5e00
	s_addc_u32 s27, s11, 0
	s_add_u32 s28, s10, 0x5f00
	s_addc_u32 s29, s11, 0
	s_add_u32 s30, s10, 0x6000
	s_addc_u32 s31, s11, 0
	s_add_u32 s34, s10, 0x6100
	s_addc_u32 s35, s11, 0
	s_add_u32 s36, s10, 0x6200
	s_addc_u32 s37, s11, 0
	s_add_u32 s38, s10, 0x6300
	s_addc_u32 s39, s11, 0
	s_ashr_i32 s96, s33, 31
	v_writelane_b32 v241, s0, 6
	s_cmp_gt_u32 s73, 8
	s_nop 0
	v_writelane_b32 v241, s1, 7
	s_cselect_b64 s[0:1], -1, 0
	v_writelane_b32 v241, s0, 8
	s_cmp_lt_i32 s92, s33
	s_nop 0
	v_writelane_b32 v241, s1, 9
	s_cbranch_scc1 .LBB0_1992
	v_mov_b32_e32 v104, v148
	v_add_u32_e32 v105, 0x2000, v104
	v_add_u32_e32 v106, 0x4000, v104
	v_add_u32_e32 v107, 0x6000, v104
	v_add_u32_e32 v108, 0x8000, v104
	v_add_u32_e32 v109, 0xa000, v104
	v_add_u32_e32 v110, 0xc000, v104
	v_add_u32_e32 v111, 0xe000, v104
	v_add_u32_e32 v112, 0x10000, v104
	v_add_u32_e32 v113, 0x12000, v104
	v_add_u32_e32 v114, 0x14000, v104
	v_add_u32_e32 v115, 0x16000, v104
	v_add_u32_e32 v116, 0x18000, v104
	v_add_u32_e32 v117, 0x1a000, v104
	v_add_u32_e32 v118, 0x1c000, v104
	v_add_u32_e32 v119, 0x1e000, v104
	v_lshrrev_b32_e32 v5, 10, v148
	v_readlane_b32 s56, v242, 43
	v_readlane_b32 s57, v242, 44
	v_readlane_b32 s60, v242, 2
	v_readlane_b32 s61, v242, 3
	v_readlane_b32 s66, v242, 4
	v_readlane_b32 s67, v242, 5
	v_readlane_b32 s68, v242, 25
	v_readfirstlane_b32 s70, v5
	v_mov_b32_e32 v2, 0
	v_mov_b32_e32 v3, 16
	v_mov_b32_e32 v6, 0x20180
	s_mov_b32 s64, 0x10478000
	s_mov_b32 s65, 0x30478000
	s_add_u32 s66, s66, 0x5400
	s_addc_u32 s67, s67, 0
	v_readlane_b32 s69, v242, 57
	s_nop 3
	s_mul_i32 s68, s68, s69
	s_mov_b64 s[62:63], exec
	s_mov_b32 s71, 0
	s_cmp_lg_u32 s70, 0
	s_cbranch_scc1 .Lce_first_done_P7
	s_mov_b64 exec, 1
	global_atomic_add v4, v2, v3, s[56:57] sc0
	s_waitcnt vmcnt(0)
	ds_write_b32 v6, v4
	s_waitcnt lgkmcnt(0)
	s_mov_b64 exec, s[62:63]
